# RG-LRU units: dropped two redundant workgroup barriers per superchunk (the one before the conv stage, and the pre-epilogue one for the first sub-chunk: both already ordered by neighbouring barriers)
# baseline (speedup 1.0000x reference)
.LBB0_463:
	s_waitcnt lgkmcnt(0)
	global_load_dwordx4 v[8:11], v[76:77], off
	global_load_dwordx4 v[16:19], v[78:79], off
	global_load_dwordx4 v[12:15], v[78:79], off offset:2048
	global_load_dwordx4 v[4:7], v[80:81], off
	global_load_dwordx4 v[0:3], v[82:83], off
	v_xor_b32_e32 v64, s26, v128
	s_xor_b64 s[24:25], s[0:1], -1
	v_lshl_or_b32 v175, v64, 7, v130
	s_mov_b64 s[40:41], -1
	s_mov_b32 s27, 0
	s_waitcnt vmcnt(3)
	v_pk_fma_f32 v[60:61], v[60:61], v[18:19], v[10:11]
	v_pk_fma_f32 v[62:63], v[62:63], v[16:17], v[8:9]
	s_waitcnt vmcnt(2)
	v_pk_fma_f32 v[60:61], v[56:57], v[14:15], v[60:61]
	v_pk_fma_f32 v[62:63], v[58:59], v[12:13], v[62:63]
	s_waitcnt vmcnt(1)
	v_pk_fma_f32 v[60:61], v[52:53], v[6:7], v[60:61]
	v_pk_fma_f32 v[62:63], v[54:55], v[4:5], v[62:63]
	s_waitcnt vmcnt(0)
	v_pk_fma_f32 v[60:61], v[48:49], v[2:3], v[60:61]
	v_pk_fma_f32 v[62:63], v[50:51], v[0:1], v[62:63]
	v_pk_fma_f32 v[56:57], v[56:57], v[18:19], v[10:11]
	v_pk_fma_f32 v[58:59], v[58:59], v[16:17], v[8:9]
	v_pk_fma_f32 v[56:57], v[52:53], v[14:15], v[56:57]
	v_pk_fma_f32 v[58:59], v[54:55], v[12:13], v[58:59]
	v_pk_fma_f32 v[56:57], v[48:49], v[6:7], v[56:57]
	v_pk_fma_f32 v[58:59], v[50:51], v[4:5], v[58:59]
	v_pk_fma_f32 v[56:57], v[40:41], v[2:3], v[56:57]
	v_pk_fma_f32 v[58:59], v[44:45], v[0:1], v[58:59]
	v_cvt_pk_bf16_f32 v61, v60, v61
	v_cvt_pk_bf16_f32 v60, v62, v63
	v_pk_fma_f32 v[52:53], v[52:53], v[18:19], v[10:11]
	v_pk_fma_f32 v[54:55], v[54:55], v[16:17], v[8:9]
	v_pk_fma_f32 v[52:53], v[48:49], v[14:15], v[52:53]
	v_pk_fma_f32 v[54:55], v[50:51], v[12:13], v[54:55]
	v_pk_fma_f32 v[52:53], v[40:41], v[6:7], v[52:53]
	v_pk_fma_f32 v[54:55], v[44:45], v[4:5], v[54:55]
	v_cvt_pk_bf16_f32 v57, v56, v57
	v_cvt_pk_bf16_f32 v56, v58, v59
	v_pk_fma_f32 v[52:53], v[32:33], v[2:3], v[52:53]
	v_pk_fma_f32 v[54:55], v[36:37], v[0:1], v[54:55]
	ds_write2_b64 v228, v[60:61], v[56:57] offset1:16
	v_pk_fma_f32 v[48:49], v[48:49], v[18:19], v[10:11]
	v_pk_fma_f32 v[50:51], v[50:51], v[16:17], v[8:9]
	v_pk_fma_f32 v[48:49], v[40:41], v[14:15], v[48:49]
	v_pk_fma_f32 v[50:51], v[44:45], v[12:13], v[50:51]
	v_pk_fma_f32 v[48:49], v[32:33], v[6:7], v[48:49]
	v_pk_fma_f32 v[50:51], v[36:37], v[4:5], v[50:51]
	v_cvt_pk_bf16_f32 v53, v52, v53
	v_cvt_pk_bf16_f32 v52, v54, v55
	v_pk_fma_f32 v[48:49], v[24:25], v[2:3], v[48:49]
	v_pk_fma_f32 v[50:51], v[28:29], v[0:1], v[50:51]
	ds_write_b64 v229, v[52:53]
	v_pk_fma_f32 v[40:41], v[40:41], v[18:19], v[10:11]
	v_pk_fma_f32 v[44:45], v[44:45], v[16:17], v[8:9]
	v_pk_fma_f32 v[40:41], v[32:33], v[14:15], v[40:41]
	v_pk_fma_f32 v[44:45], v[36:37], v[12:13], v[44:45]
	v_pk_fma_f32 v[40:41], v[24:25], v[6:7], v[40:41]
	v_pk_fma_f32 v[44:45], v[28:29], v[4:5], v[44:45]
	v_cvt_pk_bf16_f32 v49, v48, v49
	v_cvt_pk_bf16_f32 v48, v50, v51
	v_pk_fma_f32 v[40:41], v[20:21], v[2:3], v[40:41]
	v_pk_fma_f32 v[44:45], v[22:23], v[0:1], v[44:45]
	ds_write_b64 v230, v[48:49]
	v_pk_fma_f32 v[32:33], v[32:33], v[18:19], v[10:11]
	v_pk_fma_f32 v[36:37], v[36:37], v[16:17], v[8:9]
	v_pk_fma_f32 v[32:33], v[24:25], v[14:15], v[32:33]
	v_pk_fma_f32 v[36:37], v[28:29], v[12:13], v[36:37]
	v_pk_fma_f32 v[32:33], v[20:21], v[6:7], v[32:33]
	v_pk_fma_f32 v[36:37], v[22:23], v[4:5], v[36:37]
	v_cvt_pk_bf16_f32 v41, v40, v41
	v_cvt_pk_bf16_f32 v40, v44, v45
	v_pk_fma_f32 v[32:33], v[26:27], v[2:3], v[32:33]
	v_pk_fma_f32 v[36:37], v[30:31], v[0:1], v[36:37]
	ds_write_b64 v231, v[40:41]
	v_pk_fma_f32 v[24:25], v[24:25], v[18:19], v[10:11]
	v_pk_fma_f32 v[28:29], v[28:29], v[16:17], v[8:9]
	v_pk_fma_f32 v[10:11], v[20:21], v[18:19], v[10:11]
	v_pk_fma_f32 v[8:9], v[22:23], v[16:17], v[8:9]
	v_pk_fma_f32 v[24:25], v[20:21], v[14:15], v[24:25]
	v_pk_fma_f32 v[28:29], v[22:23], v[12:13], v[28:29]
	v_pk_fma_f32 v[10:11], v[26:27], v[14:15], v[10:11]
	v_pk_fma_f32 v[8:9], v[30:31], v[12:13], v[8:9]
	v_pk_fma_f32 v[24:25], v[26:27], v[6:7], v[24:25]
	v_pk_fma_f32 v[28:29], v[30:31], v[4:5], v[28:29]
	v_pk_fma_f32 v[6:7], v[34:35], v[6:7], v[10:11]
	v_pk_fma_f32 v[4:5], v[38:39], v[4:5], v[8:9]
	v_cvt_pk_bf16_f32 v33, v32, v33
	v_cvt_pk_bf16_f32 v32, v36, v37
	v_pk_fma_f32 v[24:25], v[34:35], v[2:3], v[24:25]
	v_pk_fma_f32 v[28:29], v[38:39], v[0:1], v[28:29]
	v_pk_fma_f32 v[2:3], v[42:43], v[2:3], v[6:7]
	v_pk_fma_f32 v[0:1], v[46:47], v[0:1], v[4:5]
	ds_write_b64 v232, v[32:33]
	v_and_b32_sdwa v5, v0, v170 dst_sel:DWORD dst_unused:UNUSED_PAD src0_sel:WORD_1 src1_sel:DWORD
	v_add3_u32 v0, v0, v5, s56
	v_and_b32_sdwa v5, v1, v170 dst_sel:DWORD dst_unused:UNUSED_PAD src0_sel:WORD_1 src1_sel:DWORD
	v_add3_u32 v1, v1, v5, s56
	v_and_b32_e32 v4, 0xffff0000, v1
	v_cvt_pk_bf16_f32 v25, v24, v25
	v_cvt_pk_bf16_f32 v24, v28, v29
	v_cvt_pk_bf16_f32 v1, v2, v3
	v_or_b32_sdwa v0, v4, v0 dst_sel:DWORD dst_unused:UNUSED_PAD src0_sel:DWORD src1_sel:WORD_1
	ds_write_b64 v233, v[24:25]
	ds_write_b64 v234, v[0:1]
	global_load_dwordx4 v[40:43], v[140:141], off offset:3072
	global_load_dwordx4 v[36:39], v[142:143], off offset:3072
	global_load_dwordx4 v[32:35], v[144:145], off offset:3072
	global_load_dwordx4 v[28:31], v[146:147], off offset:3072
	global_load_dwordx4 v[24:27], v[148:149], off offset:3072
	global_load_dwordx4 v[20:23], v[150:151], off offset:3072
	global_load_dwordx4 v[16:19], v[152:153], off offset:3072
	global_load_dwordx4 v[12:15], v[154:155], off offset:3072
	global_load_dwordx4 v[8:11], v[156:157], off offset:3072
	global_load_dwordx4 v[4:7], v[158:159], off offset:3072
	global_load_dwordx4 v[0:3], v[160:161], off offset:3072
	s_waitcnt lgkmcnt(0)
	s_barrier
	s_branch .LBB0_465

.LBB0_469:
	v_add_u32_e32 v60, v193, v207
	ds_read_b128 v[48:51], v60 offset:16384
	ds_read_b128 v[52:55], v60 offset:18432
	ds_read_b128 v[56:59], v60 offset:20480
	ds_read_b128 v[60:63], v60 offset:22528
	v_add_u32_e32 v44, s26, v192
	v_lshl_add_u32 v179, v44, 7, 0
	v_add_u32_e32 v44, v179, v207
	s_waitcnt lgkmcnt(4)
	ds_read_b128 v[44:47], v44
	v_add_u32_e32 v68, v193, v208
	ds_read_b128 v[64:67], v68 offset:16384
	s_waitcnt lgkmcnt(1)
	v_mfma_f32_16x16x32_bf16 v[48:51], v[48:51], v[44:47], 0
	v_add3_u32 v162, v179, v212, v213
	v_mfma_f32_16x16x32_bf16 v[52:55], v[52:55], v[44:47], 0
	v_mfma_f32_16x16x32_bf16 v[56:59], v[56:59], v[44:47], 0
	v_mfma_f32_16x16x32_bf16 v[44:47], v[60:63], v[44:47], 0
	v_add_u32_e32 v60, v179, v208
	ds_read_b128 v[60:63], v60
	s_waitcnt lgkmcnt(0)
	v_mfma_f32_16x16x32_bf16 v[64:67], v[64:67], v[60:63], v[48:51]
	s_nop 2
	ds_read_b128 v[48:51], v68 offset:18432
	s_waitcnt lgkmcnt(0)
	v_mfma_f32_16x16x32_bf16 v[48:51], v[48:51], v[60:63], v[52:55]
	s_nop 2
	ds_read_b128 v[52:55], v68 offset:20480
	s_waitcnt lgkmcnt(0)
	v_mfma_f32_16x16x32_bf16 v[52:55], v[52:55], v[60:63], v[56:59]
	s_nop 2
	ds_read_b128 v[56:59], v68 offset:22528
	s_waitcnt lgkmcnt(0)
	s_cmp_eq_u32 s27, 0
	s_cbranch_scc1 .Llru32_noba
	s_barrier
.Llru32_noba:
	v_mfma_f32_16x16x32_bf16 v[44:47], v[56:59], v[60:63], v[44:47]
	ds_read_b128 v[68:71], v209
	ds_read_b128 v[60:63], v210
	ds_read_b128 v[56:59], v211
	ds_read_b64 v[164:165], v162
	s_waitcnt lgkmcnt(3)
	v_add_f32_e32 v64, v64, v68
	v_mul_f32_e32 v64, 0xbfb8aa3b, v64
	v_exp_f32_e32 v64, v64
	s_waitcnt lgkmcnt(2)
	v_add_f32_e32 v52, v52, v60
	v_mul_f32_e32 v52, 0xbfb8aa3b, v52
	v_exp_f32_e32 v60, v52
	v_add_f32_e32 v64, 1.0, v64
	v_div_scale_f32 v68, s[0:1], v64, v64, 1.0
	v_rcp_f32_e32 v180, v68
	v_add_f32_e32 v53, v53, v61
	v_mul_f32_e32 v53, 0xbfb8aa3b, v53
	v_exp_f32_e32 v61, v53
	v_fma_f32 v181, -v68, v180, 1.0
	v_fmac_f32_e32 v180, v181, v180
	v_div_scale_f32 v181, vcc, 1.0, v64, 1.0
	v_mul_f32_e32 v182, v181, v180
	v_fma_f32 v186, -v68, v182, v181
	v_fmac_f32_e32 v182, v186, v180
	v_fma_f32 v68, -v68, v182, v181
	v_div_fmas_f32 v68, v68, v180, v182
	v_div_fixup_f32 v64, v68, v64, 1.0
	v_mul_f32_e32 v52, 0xc1000000, v64
	s_waitcnt lgkmcnt(1)
	v_mul_f32_e32 v52, v56, v52
	v_mul_f32_e32 v52, 0x3fb8aa3b, v52
	v_exp_f32_e32 v52, v52
	v_add_f32_e32 v54, v54, v62
	v_mul_f32_e32 v54, 0xbfb8aa3b, v54
	v_exp_f32_e32 v62, v54
	v_fma_f32 v56, -v52, v52, 1.0
	v_max_f32_e32 v56, 0, v56
	v_cmp_gt_f32_e32 vcc, s10, v56
	v_mul_f32_e32 v64, 0x4f800000, v56
	v_add_f32_e32 v55, v55, v63
	v_cndmask_b32_e32 v56, v56, v64, vcc
	v_sqrt_f32_e32 v64, v56
	v_mul_f32_e32 v55, 0xbfb8aa3b, v55
	v_exp_f32_e32 v63, v55
	v_pk_add_f32 v[60:61], v[60:61], 1.0 op_sel_hi:[1,0]
	v_add_u32_e32 v68, -1, v64
	v_fma_f32 v180, -v68, v64, v56
	v_cmp_ge_f32_e64 s[0:1], 0, v180
	v_add_u32_e32 v180, 1, v64
	v_pk_add_f32 v[62:63], v[62:63], 1.0 op_sel_hi:[1,0]
	v_cndmask_b32_e64 v68, v64, v68, s[0:1]
	v_fma_f32 v64, -v180, v64, v56
	v_cmp_lt_f32_e64 s[0:1], 0, v64
	s_waitcnt lgkmcnt(0)
	v_lshlrev_b32_e32 v162, 16, v164
	v_and_b32_e32 v163, 0xffff0000, v164
	v_cndmask_b32_e64 v64, v68, v180, s[0:1]
	v_mul_f32_e32 v68, 0x37800000, v64
	v_cndmask_b32_e32 v64, v64, v68, vcc
	v_cmp_class_f32_e32 vcc, v56, v169
	v_lshlrev_b32_e32 v164, 16, v165
	v_and_b32_e32 v165, 0xffff0000, v165
	v_cndmask_b32_e32 v56, v64, v56, vcc
	v_add_f32_e32 v64, v65, v69
	v_mul_f32_e32 v64, 0xbfb8aa3b, v64
	v_exp_f32_e32 v64, v64
	s_nop 0
	v_add_f32_e32 v64, 1.0, v64
	v_div_scale_f32 v65, s[0:1], v64, v64, 1.0
	v_rcp_f32_e32 v68, v65
	s_nop 0
	v_fma_f32 v69, -v65, v68, 1.0
	v_fmac_f32_e32 v68, v69, v68
	v_div_scale_f32 v69, vcc, 1.0, v64, 1.0
	v_mul_f32_e32 v180, v69, v68
	v_fma_f32 v181, -v65, v180, v69
	v_fmac_f32_e32 v180, v181, v68
	v_fma_f32 v65, -v65, v180, v69
	v_div_fmas_f32 v65, v65, v68, v180
	v_div_fixup_f32 v64, v65, v64, 1.0
	v_mul_f32_e32 v53, 0xc1000000, v64
	v_mul_f32_e32 v53, v57, v53
	v_mul_f32_e32 v53, 0x3fb8aa3b, v53
	v_exp_f32_e32 v53, v53
	s_nop 0
	v_fma_f32 v57, -v53, v53, 1.0
	v_max_f32_e32 v57, 0, v57
	v_cmp_gt_f32_e32 vcc, s10, v57
	v_mul_f32_e32 v64, 0x4f800000, v57
	s_nop 0
	v_cndmask_b32_e32 v57, v57, v64, vcc
	v_sqrt_f32_e32 v64, v57
	s_nop 0
	v_add_u32_e32 v65, -1, v64
	v_fma_f32 v68, -v65, v64, v57
	v_cmp_ge_f32_e64 s[0:1], 0, v68
	v_add_u32_e32 v68, 1, v64
	s_nop 0
	v_cndmask_b32_e64 v65, v64, v65, s[0:1]
	v_fma_f32 v64, -v68, v64, v57
	v_cmp_lt_f32_e64 s[0:1], 0, v64
	s_nop 1
	v_cndmask_b32_e64 v64, v65, v68, s[0:1]
	v_mul_f32_e32 v65, 0x37800000, v64
	v_cndmask_b32_e32 v64, v64, v65, vcc
	v_cmp_class_f32_e32 vcc, v57, v169
	s_nop 1
	v_cndmask_b32_e32 v57, v64, v57, vcc
	v_add_f32_e32 v64, v66, v70
	v_mul_f32_e32 v64, 0xbfb8aa3b, v64
	v_exp_f32_e32 v64, v64
	s_nop 0
	v_add_f32_e32 v64, 1.0, v64
	v_div_scale_f32 v65, s[0:1], v64, v64, 1.0
	v_rcp_f32_e32 v66, v65
	s_nop 0
	v_fma_f32 v68, -v65, v66, 1.0
	v_fmac_f32_e32 v66, v68, v66
	v_div_scale_f32 v68, vcc, 1.0, v64, 1.0
	v_mul_f32_e32 v69, v68, v66
	v_fma_f32 v70, -v65, v69, v68
	v_fmac_f32_e32 v69, v70, v66
	v_fma_f32 v65, -v65, v69, v68
	v_div_fmas_f32 v65, v65, v66, v69
	v_div_fixup_f32 v64, v65, v64, 1.0
	v_mul_f32_e32 v54, 0xc1000000, v64
	v_mul_f32_e32 v54, v58, v54
	v_mul_f32_e32 v54, 0x3fb8aa3b, v54
	v_exp_f32_e32 v54, v54
	s_nop 0
	v_fma_f32 v58, -v54, v54, 1.0
	v_max_f32_e32 v58, 0, v58
	v_cmp_gt_f32_e32 vcc, s10, v58
	v_mul_f32_e32 v64, 0x4f800000, v58
	s_nop 0
	v_cndmask_b32_e32 v58, v58, v64, vcc
	v_sqrt_f32_e32 v64, v58
	s_nop 0
	v_add_u32_e32 v65, -1, v64
	v_fma_f32 v66, -v65, v64, v58
	v_cmp_ge_f32_e64 s[0:1], 0, v66
	v_add_u32_e32 v66, 1, v64
	s_nop 0
	v_cndmask_b32_e64 v65, v64, v65, s[0:1]
	v_fma_f32 v64, -v66, v64, v58
	v_cmp_lt_f32_e64 s[0:1], 0, v64
	s_nop 1
	v_cndmask_b32_e64 v64, v65, v66, s[0:1]
	v_mul_f32_e32 v65, 0x37800000, v64
	v_cndmask_b32_e32 v64, v64, v65, vcc
	v_cmp_class_f32_e32 vcc, v58, v169
	s_nop 1
	v_cndmask_b32_e32 v58, v64, v58, vcc
	v_add_f32_e32 v64, v67, v71
	v_mul_f32_e32 v64, 0xbfb8aa3b, v64
	v_exp_f32_e32 v64, v64
	s_nop 0
	v_add_f32_e32 v64, 1.0, v64
	v_div_scale_f32 v65, s[0:1], v64, v64, 1.0
	v_rcp_f32_e32 v66, v65
	s_nop 0
	v_fma_f32 v67, -v65, v66, 1.0
	v_fmac_f32_e32 v66, v67, v66
	v_div_scale_f32 v67, vcc, 1.0, v64, 1.0
	v_mul_f32_e32 v68, v67, v66
	v_fma_f32 v69, -v65, v68, v67
	v_fmac_f32_e32 v68, v69, v66
	v_fma_f32 v65, -v65, v68, v67
	v_div_fmas_f32 v65, v65, v66, v68
	v_div_fixup_f32 v64, v65, v64, 1.0
	v_mul_f32_e32 v55, 0xc1000000, v64
	v_mul_f32_e32 v55, v59, v55
	v_mul_f32_e32 v55, 0x3fb8aa3b, v55
	v_exp_f32_e32 v55, v55
	s_nop 0
	v_fma_f32 v59, -v55, v55, 1.0
	v_max_f32_e32 v59, 0, v59
	v_cmp_gt_f32_e32 vcc, s10, v59
	v_mul_f32_e32 v64, 0x4f800000, v59
	s_nop 0
	v_cndmask_b32_e32 v59, v59, v64, vcc
	v_sqrt_f32_e32 v64, v59
	s_nop 0
	v_add_u32_e32 v65, -1, v64
	v_fma_f32 v66, -v65, v64, v59
	v_cmp_ge_f32_e64 s[0:1], 0, v66
	v_add_u32_e32 v66, 1, v64
	s_nop 0
	v_cndmask_b32_e64 v65, v64, v65, s[0:1]
	v_fma_f32 v64, -v66, v64, v59
	v_cmp_lt_f32_e64 s[0:1], 0, v64
	s_nop 1
	v_cndmask_b32_e64 v64, v65, v66, s[0:1]
	v_mul_f32_e32 v65, 0x37800000, v64
	v_cndmask_b32_e32 v64, v64, v65, vcc
	v_cmp_class_f32_e32 vcc, v59, v169
	s_nop 1
	v_cndmask_b32_e32 v59, v64, v59, vcc
	v_div_scale_f32 v64, s[0:1], v63, v63, 1.0
	v_rcp_f32_e32 v65, v64
	s_nop 0
	v_fma_f32 v66, -v64, v65, 1.0
	v_fmac_f32_e32 v65, v66, v65
	v_div_scale_f32 v66, vcc, 1.0, v63, 1.0
	v_mul_f32_e32 v67, v66, v65
	v_fma_f32 v68, -v64, v67, v66
	v_fmac_f32_e32 v67, v68, v65
	v_fma_f32 v64, -v64, v67, v66
	v_div_fmas_f32 v64, v64, v65, v67
	v_div_fixup_f32 v63, v64, v63, 1.0
	v_div_scale_f32 v64, s[0:1], v62, v62, 1.0
	v_rcp_f32_e32 v65, v64
	s_nop 0
	v_fma_f32 v66, -v64, v65, 1.0
	v_fmac_f32_e32 v65, v66, v65
	v_div_scale_f32 v66, vcc, 1.0, v62, 1.0
	v_mul_f32_e32 v67, v66, v65
	v_fma_f32 v68, -v64, v67, v66
	v_fmac_f32_e32 v67, v68, v65
	v_fma_f32 v64, -v64, v67, v66
	v_div_fmas_f32 v64, v64, v65, v67
	v_div_fixup_f32 v62, v64, v62, 1.0
	v_div_scale_f32 v64, s[0:1], v61, v61, 1.0
	v_rcp_f32_e32 v65, v64
	v_pk_mul_f32 v[58:59], v[62:63], v[58:59]
	v_fma_f32 v66, -v64, v65, 1.0
	v_fmac_f32_e32 v65, v66, v65
	v_div_scale_f32 v66, vcc, 1.0, v61, 1.0
	v_mul_f32_e32 v67, v66, v65
	v_fma_f32 v68, -v64, v67, v66
	v_fmac_f32_e32 v67, v68, v65
	v_fma_f32 v64, -v64, v67, v66
	v_div_fmas_f32 v64, v64, v65, v67
	v_div_fixup_f32 v61, v64, v61, 1.0
	v_div_scale_f32 v64, s[0:1], v60, v60, 1.0
	v_rcp_f32_e32 v65, v64
	v_pk_mul_f32 v[58:59], v[58:59], v[164:165]
	v_fma_f32 v66, -v64, v65, 1.0
	v_fmac_f32_e32 v65, v66, v65
	v_div_scale_f32 v66, vcc, 1.0, v60, 1.0
	v_mul_f32_e32 v67, v66, v65
	v_fma_f32 v68, -v64, v67, v66
	v_fmac_f32_e32 v67, v68, v65
	v_fma_f32 v64, -v64, v67, v66
	v_div_fmas_f32 v64, v64, v65, v67
	v_div_fixup_f32 v60, v64, v60, 1.0
	v_pk_mul_f32 v[56:57], v[60:61], v[56:57]
	v_add3_u32 v64, v179, v218, v213
	v_pk_mul_f32 v[56:57], v[56:57], v[162:163]
	ds_write_b128 v214, v[52:55] offset:32768
	ds_write_b128 v214, v[56:59] offset:50176
	ds_read_b128 v[60:63], v215
	ds_read_b128 v[56:59], v216
	ds_read_b128 v[52:55], v217
	ds_read_b64 v[66:67], v64
	s_waitcnt lgkmcnt(3)
	v_add_f32_e32 v48, v48, v60
	v_mul_f32_e32 v48, 0xbfb8aa3b, v48
	v_exp_f32_e32 v48, v48
	s_waitcnt lgkmcnt(2)
	v_add_f32_e32 v44, v44, v56
	v_mul_f32_e32 v44, 0xbfb8aa3b, v44
	v_exp_f32_e32 v56, v44
	v_add_f32_e32 v48, 1.0, v48
	v_div_scale_f32 v60, s[0:1], v48, v48, 1.0
	v_rcp_f32_e32 v68, v60
	v_add_f32_e32 v49, v49, v61
	v_mul_f32_e32 v49, 0xbfb8aa3b, v49
	v_exp_f32_e32 v49, v49
	v_fma_f32 v69, -v60, v68, 1.0
	v_fmac_f32_e32 v68, v69, v68
	v_div_scale_f32 v69, vcc, 1.0, v48, 1.0
	v_mul_f32_e32 v70, v69, v68
	v_fma_f32 v71, -v60, v70, v69
	v_fmac_f32_e32 v70, v71, v68
	v_fma_f32 v60, -v60, v70, v69
	v_div_fmas_f32 v60, v60, v68, v70
	v_div_fixup_f32 v48, v60, v48, 1.0
	v_mul_f32_e32 v44, 0xc1000000, v48
	s_waitcnt lgkmcnt(1)
	v_mul_f32_e32 v44, v52, v44
	v_mul_f32_e32 v44, 0x3fb8aa3b, v44
	v_exp_f32_e32 v44, v44
	v_add_f32_e32 v49, 1.0, v49
	v_add_f32_e32 v45, v45, v57
	v_mul_f32_e32 v45, 0xbfb8aa3b, v45
	v_fma_f32 v48, -v44, v44, 1.0
	v_max_f32_e32 v48, 0, v48
	v_cmp_gt_f32_e32 vcc, s10, v48
	v_mul_f32_e32 v52, 0x4f800000, v48
	v_exp_f32_e32 v57, v45
	v_cndmask_b32_e32 v48, v48, v52, vcc
	v_sqrt_f32_e32 v52, v48
	v_add_f32_e32 v50, v50, v62
	v_mul_f32_e32 v50, 0xbfb8aa3b, v50
	v_exp_f32_e32 v50, v50
	v_add_u32_e32 v60, -1, v52
	v_fma_f32 v68, -v60, v52, v48
	v_cmp_ge_f32_e64 s[0:1], 0, v68
	v_add_u32_e32 v68, 1, v52
	v_add_f32_e32 v50, 1.0, v50
	v_cndmask_b32_e64 v60, v52, v60, s[0:1]
	v_fma_f32 v52, -v68, v52, v48
	v_cmp_lt_f32_e64 s[0:1], 0, v52
	v_add_f32_e32 v46, v46, v58
	v_mul_f32_e32 v46, 0xbfb8aa3b, v46
	v_cndmask_b32_e64 v52, v60, v68, s[0:1]
	v_mul_f32_e32 v60, 0x37800000, v52
	v_cndmask_b32_e32 v52, v52, v60, vcc
	v_cmp_class_f32_e32 vcc, v48, v169
	v_add_f32_e32 v51, v51, v63
	v_mul_f32_e32 v51, 0xbfb8aa3b, v51
	v_cndmask_b32_e32 v48, v52, v48, vcc
	v_div_scale_f32 v52, s[0:1], v49, v49, 1.0
	v_rcp_f32_e32 v60, v52
	v_exp_f32_e32 v51, v51
	v_add_f32_e32 v47, v47, v59
	v_mul_f32_e32 v47, 0xbfb8aa3b, v47
	v_fma_f32 v61, -v52, v60, 1.0
	v_fmac_f32_e32 v60, v61, v60
	v_div_scale_f32 v61, vcc, 1.0, v49, 1.0
	v_mul_f32_e32 v68, v61, v60
	v_fma_f32 v69, -v52, v68, v61
	v_fmac_f32_e32 v68, v69, v60
	v_fma_f32 v52, -v52, v68, v61
	v_div_fmas_f32 v52, v52, v60, v68
	v_div_fixup_f32 v49, v52, v49, 1.0
	v_mul_f32_e32 v45, 0xc1000000, v49
	v_mul_f32_e32 v45, v53, v45
	v_mul_f32_e32 v45, 0x3fb8aa3b, v45
	v_exp_f32_e32 v45, v45
	v_add_f32_e32 v51, 1.0, v51
	s_waitcnt lgkmcnt(0)
	v_lshlrev_b32_e32 v64, 16, v66
	v_and_b32_e32 v65, 0xffff0000, v66
	v_fma_f32 v49, -v45, v45, 1.0
	v_max_f32_e32 v49, 0, v49
	v_cmp_gt_f32_e32 vcc, s10, v49
	v_mul_f32_e32 v52, 0x4f800000, v49
	v_lshlrev_b32_e32 v66, 16, v67
	v_cndmask_b32_e32 v49, v49, v52, vcc
	v_sqrt_f32_e32 v52, v49
	v_and_b32_e32 v67, 0xffff0000, v67
	v_add_u32_e32 v53, -1, v52
	v_fma_f32 v60, -v53, v52, v49
	v_cmp_ge_f32_e64 s[0:1], 0, v60
	v_add_u32_e32 v60, 1, v52
	s_nop 0
	v_cndmask_b32_e64 v53, v52, v53, s[0:1]
	v_fma_f32 v52, -v60, v52, v49
	v_cmp_lt_f32_e64 s[0:1], 0, v52
	s_nop 1
	v_cndmask_b32_e64 v52, v53, v60, s[0:1]
	v_mul_f32_e32 v53, 0x37800000, v52
	v_cndmask_b32_e32 v52, v52, v53, vcc
	v_cmp_class_f32_e32 vcc, v49, v169
	s_nop 1
	v_cndmask_b32_e32 v49, v52, v49, vcc
	v_div_scale_f32 v52, s[0:1], v50, v50, 1.0
	v_rcp_f32_e32 v53, v52
	s_nop 0
	v_fma_f32 v60, -v52, v53, 1.0
	v_fmac_f32_e32 v53, v60, v53
	v_div_scale_f32 v60, vcc, 1.0, v50, 1.0
	v_mul_f32_e32 v61, v60, v53
	v_fma_f32 v62, -v52, v61, v60
	v_fmac_f32_e32 v61, v62, v53
	v_fma_f32 v52, -v52, v61, v60
	v_div_fmas_f32 v52, v52, v53, v61
	v_div_fixup_f32 v50, v52, v50, 1.0
	v_exp_f32_e32 v52, v46
	v_mul_f32_e32 v46, 0xc1000000, v50
	v_mul_f32_e32 v46, v54, v46
	v_mul_f32_e32 v46, 0x3fb8aa3b, v46
	v_exp_f32_e32 v46, v46
	s_nop 0
	v_fma_f32 v50, -v46, v46, 1.0
	v_max_f32_e32 v50, 0, v50
	v_cmp_gt_f32_e32 vcc, s10, v50
	v_mul_f32_e32 v53, 0x4f800000, v50
	s_nop 0
	v_cndmask_b32_e32 v50, v50, v53, vcc
	v_sqrt_f32_e32 v53, v50
	s_nop 0
	v_add_u32_e32 v54, -1, v53
	v_fma_f32 v58, -v54, v53, v50
	v_cmp_ge_f32_e64 s[0:1], 0, v58
	v_add_u32_e32 v58, 1, v53
	s_nop 0
	v_cndmask_b32_e64 v54, v53, v54, s[0:1]
	v_fma_f32 v53, -v58, v53, v50
	v_cmp_lt_f32_e64 s[0:1], 0, v53
	s_nop 1
	v_cndmask_b32_e64 v53, v54, v58, s[0:1]
	v_mul_f32_e32 v54, 0x37800000, v53
	v_cndmask_b32_e32 v53, v53, v54, vcc
	v_cmp_class_f32_e32 vcc, v50, v169
	s_nop 1
	v_cndmask_b32_e32 v50, v53, v50, vcc
	v_div_scale_f32 v53, s[0:1], v51, v51, 1.0
	v_rcp_f32_e32 v54, v53
	s_nop 0
	v_fma_f32 v58, -v53, v54, 1.0
	v_fmac_f32_e32 v54, v58, v54
	v_div_scale_f32 v58, vcc, 1.0, v51, 1.0
	v_mul_f32_e32 v60, v58, v54
	v_fma_f32 v61, -v53, v60, v58
	v_fmac_f32_e32 v60, v61, v54
	v_fma_f32 v53, -v53, v60, v58
	v_div_fmas_f32 v53, v53, v54, v60
	v_div_fixup_f32 v51, v53, v51, 1.0
	v_exp_f32_e32 v53, v47
	v_mul_f32_e32 v47, 0xc1000000, v51
	v_mul_f32_e32 v47, v55, v47
	v_mul_f32_e32 v47, 0x3fb8aa3b, v47
	v_exp_f32_e32 v47, v47
	v_pk_add_f32 v[52:53], v[52:53], 1.0 op_sel_hi:[1,0]
	v_fma_f32 v51, -v47, v47, 1.0
	v_max_f32_e32 v51, 0, v51
	v_cmp_gt_f32_e32 vcc, s10, v51
	v_mul_f32_e32 v54, 0x4f800000, v51
	s_nop 0
	v_cndmask_b32_e32 v51, v51, v54, vcc
	v_sqrt_f32_e32 v54, v51
	s_nop 0
	v_add_u32_e32 v55, -1, v54
	v_fma_f32 v58, -v55, v54, v51
	v_cmp_ge_f32_e64 s[0:1], 0, v58
	v_add_u32_e32 v58, 1, v54
	s_nop 0
	v_cndmask_b32_e64 v55, v54, v55, s[0:1]
	v_fma_f32 v54, -v58, v54, v51
	v_cmp_lt_f32_e64 s[0:1], 0, v54
	s_nop 1
	v_cndmask_b32_e64 v54, v55, v58, s[0:1]
	v_mul_f32_e32 v55, 0x37800000, v54
	v_cndmask_b32_e32 v54, v54, v55, vcc
	v_cmp_class_f32_e32 vcc, v51, v169
	s_nop 1
	v_cndmask_b32_e32 v51, v54, v51, vcc
	v_pk_add_f32 v[54:55], v[56:57], 1.0 op_sel_hi:[1,0]
	v_div_scale_f32 v56, s[0:1], v53, v53, 1.0
	v_rcp_f32_e32 v57, v56
	s_nop 0
	v_fma_f32 v58, -v56, v57, 1.0
	v_fmac_f32_e32 v57, v58, v57
	v_div_scale_f32 v58, vcc, 1.0, v53, 1.0
	v_mul_f32_e32 v59, v58, v57
	v_fma_f32 v60, -v56, v59, v58
	v_fmac_f32_e32 v59, v60, v57
	v_fma_f32 v56, -v56, v59, v58
	v_div_fmas_f32 v56, v56, v57, v59
	v_div_fixup_f32 v53, v56, v53, 1.0
	v_div_scale_f32 v56, s[0:1], v52, v52, 1.0
	v_rcp_f32_e32 v57, v56
	s_nop 0
	v_fma_f32 v58, -v56, v57, 1.0
	v_fmac_f32_e32 v57, v58, v57
	v_div_scale_f32 v58, vcc, 1.0, v52, 1.0
	v_mul_f32_e32 v59, v58, v57
	v_fma_f32 v60, -v56, v59, v58
	v_fmac_f32_e32 v59, v60, v57
	v_fma_f32 v56, -v56, v59, v58
	v_div_fmas_f32 v56, v56, v57, v59
	v_div_fixup_f32 v52, v56, v52, 1.0
	v_div_scale_f32 v56, s[0:1], v55, v55, 1.0
	v_rcp_f32_e32 v57, v56
	v_pk_mul_f32 v[50:51], v[52:53], v[50:51]
	v_fma_f32 v58, -v56, v57, 1.0
	v_fmac_f32_e32 v57, v58, v57
	v_div_scale_f32 v58, vcc, 1.0, v55, 1.0
	v_mul_f32_e32 v59, v58, v57
	v_fma_f32 v60, -v56, v59, v58
	v_fmac_f32_e32 v59, v60, v57
	v_fma_f32 v56, -v56, v59, v58
	v_div_fmas_f32 v56, v56, v57, v59
	v_div_fixup_f32 v55, v56, v55, 1.0
	v_div_scale_f32 v56, s[0:1], v54, v54, 1.0
	v_rcp_f32_e32 v57, v56
	v_pk_mul_f32 v[50:51], v[50:51], v[66:67]
	v_fma_f32 v58, -v56, v57, 1.0
	v_fmac_f32_e32 v57, v58, v57
	v_div_scale_f32 v58, vcc, 1.0, v54, 1.0
	v_mul_f32_e32 v59, v58, v57
	v_fma_f32 v60, -v56, v59, v58
	v_fmac_f32_e32 v59, v60, v57
	v_fma_f32 v56, -v56, v59, v58
	v_div_fmas_f32 v56, v56, v57, v59
	v_div_fixup_f32 v54, v56, v54, 1.0
	v_pk_mul_f32 v[48:49], v[54:55], v[48:49]
	s_nop 0
	v_pk_mul_f32 v[48:49], v[48:49], v[64:65]
	ds_write_b128 v214, v[44:47] offset:32832
	ds_write_b128 v214, v[48:51] offset:50240
	s_waitcnt lgkmcnt(0)
	s_barrier
	s_and_saveexec_b64 s[0:1], s[38:39]
	s_cbranch_execz .LBB0_472
	s_mov_b32 s28, 0
	s_and_b64 vcc, s[88:89], exec
	s_cbranch_scc0 .Lscan32_rinit
	v_mov_b32_e32 v60, v195
	ds_read_b32 v44, v60 offset:32768
	ds_read_b32 v45, v60 offset:50176
	ds_read_b32 v46, v60 offset:32912
	ds_read_b32 v47, v60 offset:50320
	ds_read_b32 v48, v60 offset:33056
	ds_read_b32 v49, v60 offset:50464
	ds_read_b32 v50, v60 offset:33200
	ds_read_b32 v51, v60 offset:50608
	ds_read_b32 v52, v60 offset:32768
	ds_read_b32 v53, v60 offset:32768
	ds_read_b32 v54, v60 offset:32768
	ds_read_b32 v55, v60 offset:32768

.LBB0_539:
	s_sub_i32 s1, 7, s24
	v_mov_b32_e32 v0, s1
	v_mov_b32_e32 v1, s24
	v_cndmask_b32_e64 v124, v0, v1, s[38:39]
	s_waitcnt lgkmcnt(0)
	global_load_dwordx4 v[8:11], v[70:71], off
	global_load_dwordx4 v[16:19], v[72:73], off
	global_load_dwordx4 v[12:15], v[72:73], off offset:2048
	global_load_dwordx4 v[4:7], v[76:77], off
	global_load_dwordx4 v[0:3], v[78:79], off
	s_mov_b32 s0, s24
	s_add_i32 s24, s24, 1
	s_cmp_lg_u32 s0, 7
	s_cselect_b32 s0, s24, 7
	s_sub_i32 s1, 7, s0
	v_lshl_add_u32 v124, v124, 7, v97
	s_mov_b64 s[2:3], -1
	s_mov_b32 s25, 0
	s_waitcnt vmcnt(3)
	v_pk_fma_f32 v[38:39], v[90:91], v[18:19], v[10:11]
	v_pk_fma_f32 v[40:41], v[92:93], v[16:17], v[8:9]
	s_waitcnt vmcnt(2)
	v_pk_fma_f32 v[38:39], v[62:63], v[14:15], v[38:39]
	v_pk_fma_f32 v[40:41], v[64:65], v[12:13], v[40:41]
	s_waitcnt vmcnt(1)
	v_pk_fma_f32 v[38:39], v[58:59], v[6:7], v[38:39]
	v_pk_fma_f32 v[40:41], v[60:61], v[4:5], v[40:41]
	s_waitcnt vmcnt(0)
	v_pk_fma_f32 v[38:39], v[54:55], v[2:3], v[38:39]
	v_pk_fma_f32 v[40:41], v[56:57], v[0:1], v[40:41]
	v_cvt_pk_bf16_f32 v39, v38, v39
	v_cvt_pk_bf16_f32 v38, v40, v41
	v_pk_fma_f32 v[40:41], v[62:63], v[18:19], v[10:11]
	v_pk_fma_f32 v[42:43], v[64:65], v[16:17], v[8:9]
	v_pk_fma_f32 v[40:41], v[58:59], v[14:15], v[40:41]
	v_pk_fma_f32 v[42:43], v[60:61], v[12:13], v[42:43]
	v_pk_fma_f32 v[40:41], v[54:55], v[6:7], v[40:41]
	v_pk_fma_f32 v[42:43], v[56:57], v[4:5], v[42:43]
	v_pk_fma_f32 v[40:41], v[50:51], v[2:3], v[40:41]
	v_pk_fma_f32 v[42:43], v[52:53], v[0:1], v[42:43]
	v_cvt_pk_bf16_f32 v41, v40, v41
	v_cvt_pk_bf16_f32 v40, v42, v43
	ds_write2_b64 v115, v[38:39], v[40:41] offset1:16
	v_pk_fma_f32 v[38:39], v[58:59], v[18:19], v[10:11]
	v_pk_fma_f32 v[40:41], v[60:61], v[16:17], v[8:9]
	v_pk_fma_f32 v[38:39], v[54:55], v[14:15], v[38:39]
	v_pk_fma_f32 v[40:41], v[56:57], v[12:13], v[40:41]
	v_pk_fma_f32 v[38:39], v[50:51], v[6:7], v[38:39]
	v_pk_fma_f32 v[40:41], v[52:53], v[4:5], v[40:41]
	v_pk_fma_f32 v[38:39], v[46:47], v[2:3], v[38:39]
	v_pk_fma_f32 v[40:41], v[48:49], v[0:1], v[40:41]
	v_cvt_pk_bf16_f32 v39, v38, v39
	v_cvt_pk_bf16_f32 v38, v40, v41
	ds_write_b64 v116, v[38:39]
	v_pk_fma_f32 v[38:39], v[54:55], v[18:19], v[10:11]
	v_pk_fma_f32 v[40:41], v[56:57], v[16:17], v[8:9]
	v_pk_fma_f32 v[38:39], v[50:51], v[14:15], v[38:39]
	v_pk_fma_f32 v[40:41], v[52:53], v[12:13], v[40:41]
	v_pk_fma_f32 v[38:39], v[46:47], v[6:7], v[38:39]
	v_pk_fma_f32 v[40:41], v[48:49], v[4:5], v[40:41]
	v_pk_fma_f32 v[38:39], v[26:27], v[2:3], v[38:39]
	v_pk_fma_f32 v[40:41], v[44:45], v[0:1], v[40:41]
	v_cvt_pk_bf16_f32 v39, v38, v39
	v_cvt_pk_bf16_f32 v38, v40, v41
	ds_write_b64 v117, v[38:39]
	v_pk_fma_f32 v[38:39], v[50:51], v[18:19], v[10:11]
	v_pk_fma_f32 v[40:41], v[52:53], v[16:17], v[8:9]
	v_pk_fma_f32 v[38:39], v[46:47], v[14:15], v[38:39]
	v_pk_fma_f32 v[40:41], v[48:49], v[12:13], v[40:41]
	v_pk_fma_f32 v[38:39], v[26:27], v[6:7], v[38:39]
	v_pk_fma_f32 v[40:41], v[44:45], v[4:5], v[40:41]
	v_pk_fma_f32 v[38:39], v[20:21], v[2:3], v[38:39]
	v_pk_fma_f32 v[40:41], v[22:23], v[0:1], v[40:41]
	v_cvt_pk_bf16_f32 v39, v38, v39
	v_cvt_pk_bf16_f32 v38, v40, v41
	ds_write_b64 v118, v[38:39]
	v_pk_fma_f32 v[38:39], v[46:47], v[18:19], v[10:11]
	v_pk_fma_f32 v[40:41], v[48:49], v[16:17], v[8:9]
	v_pk_fma_f32 v[38:39], v[26:27], v[14:15], v[38:39]
	v_pk_fma_f32 v[40:41], v[44:45], v[12:13], v[40:41]
	v_pk_fma_f32 v[38:39], v[20:21], v[6:7], v[38:39]
	v_pk_fma_f32 v[40:41], v[22:23], v[4:5], v[40:41]
	v_pk_fma_f32 v[38:39], v[24:25], v[2:3], v[38:39]
	v_pk_fma_f32 v[40:41], v[28:29], v[0:1], v[40:41]
	v_cvt_pk_bf16_f32 v39, v38, v39
	v_cvt_pk_bf16_f32 v38, v40, v41
	ds_write_b64 v119, v[38:39]
	v_pk_fma_f32 v[26:27], v[26:27], v[18:19], v[10:11]
	v_pk_fma_f32 v[38:39], v[44:45], v[16:17], v[8:9]
	v_pk_fma_f32 v[10:11], v[20:21], v[18:19], v[10:11]
	v_pk_fma_f32 v[8:9], v[22:23], v[16:17], v[8:9]
	v_pk_fma_f32 v[26:27], v[20:21], v[14:15], v[26:27]
	v_pk_fma_f32 v[38:39], v[22:23], v[12:13], v[38:39]
	v_pk_fma_f32 v[10:11], v[24:25], v[14:15], v[10:11]
	v_pk_fma_f32 v[8:9], v[28:29], v[12:13], v[8:9]
	v_pk_fma_f32 v[26:27], v[24:25], v[6:7], v[26:27]
	v_pk_fma_f32 v[38:39], v[28:29], v[4:5], v[38:39]
	v_pk_fma_f32 v[6:7], v[30:31], v[6:7], v[10:11]
	v_pk_fma_f32 v[4:5], v[32:33], v[4:5], v[8:9]
	v_pk_fma_f32 v[26:27], v[30:31], v[2:3], v[26:27]
	v_pk_fma_f32 v[38:39], v[32:33], v[0:1], v[38:39]
	v_pk_fma_f32 v[2:3], v[34:35], v[2:3], v[6:7]
	v_pk_fma_f32 v[0:1], v[36:37], v[0:1], v[4:5]
	v_and_b32_sdwa v5, v0, v170 dst_sel:DWORD dst_unused:UNUSED_PAD src0_sel:WORD_1 src1_sel:DWORD
	v_add3_u32 v0, v0, v5, s56
	v_and_b32_sdwa v5, v1, v170 dst_sel:DWORD dst_unused:UNUSED_PAD src0_sel:WORD_1 src1_sel:DWORD
	v_add3_u32 v1, v1, v5, s56
	v_and_b32_e32 v4, 0xffff0000, v1
	v_cvt_pk_bf16_f32 v27, v26, v27
	v_cvt_pk_bf16_f32 v26, v38, v39
	v_cvt_pk_bf16_f32 v1, v2, v3
	v_or_b32_sdwa v0, v4, v0 dst_sel:DWORD dst_unused:UNUSED_PAD src0_sel:DWORD src1_sel:WORD_1
	ds_write_b64 v120, v[26:27]
	ds_write_b64 v121, v[0:1]
	v_mov_b32_e32 v0, s1
	v_mov_b32_e32 v1, s0
	v_cndmask_b32_e64 v0, v0, v1, s[38:39]
	v_lshl_add_u32 v122, v0, 7, v98
	v_min_i32_e32 v0, 0x401, v122
	v_or_b32_e32 v4, 1, v122
	v_add_u32_e32 v0, -2, v0
	v_cmp_lt_i32_e32 vcc, 1, v122
	v_min_i32_e32 v5, 0x401, v4
	v_or_b32_e32 v8, 2, v122
	v_or_b32_e32 v12, 3, v122
	v_or_b32_e32 v16, 4, v122
	v_or_b32_e32 v20, 5, v122
	v_or_b32_e32 v24, 6, v122
	v_or_b32_e32 v28, 7, v122
	v_cndmask_b32_e32 v0, 0, v0, vcc
	v_add_u32_e32 v5, -2, v5
	v_cmp_lt_i32_e32 vcc, 1, v4
	v_min_i32_e32 v8, 0x401, v8
	v_min_i32_e32 v12, 0x401, v12
	v_min_i32_e32 v16, 0x401, v16
	v_min_i32_e32 v20, 0x401, v20
	v_min_i32_e32 v24, 0x401, v24
	v_min_i32_e32 v28, 0x401, v28
	v_add_u32_e32 v123, 8, v122
	v_cndmask_b32_e32 v4, 0, v5, vcc
	v_cmp_gt_i32_e32 vcc, 0, v122
	v_add_u32_e32 v8, -2, v8
	v_add_u32_e32 v12, -2, v12
	v_add_u32_e32 v16, -2, v16
	v_add_u32_e32 v20, -2, v20
	v_add_u32_e32 v24, -2, v24
	v_add_u32_e32 v28, -2, v28
	v_min_i32_e32 v32, 0x401, v123
	v_cndmask_b32_e64 v8, v8, 0, vcc
	v_cndmask_b32_e64 v12, v12, 0, vcc
	v_cndmask_b32_e64 v16, v16, 0, vcc
	v_cndmask_b32_e64 v20, v20, 0, vcc
	v_cndmask_b32_e64 v24, v24, 0, vcc
	v_cndmask_b32_e64 v28, v28, 0, vcc
	v_add_u32_e32 v32, -2, v32
	v_cmp_lt_i32_e32 vcc, 1, v123
	v_min_i32_e32 v36, 0x3f8, v122
	v_or_b32_e32 v36, 7, v36
	v_cndmask_b32_e32 v32, 0, v32, vcc
	v_cmp_lt_i32_e32 vcc, -8, v122
	v_add_u32_e32 v0, v0, v97
	v_add_u32_e32 v4, v4, v97
	v_cndmask_b32_e32 v36, 0, v36, vcc
	v_add_u32_e32 v36, v36, v97
	v_ashrrev_i32_e32 v37, 31, v36
	v_lshlrev_b64 v[36:37], 13, v[36:37]
	v_lshl_add_u64 v[36:37], v[88:89], 0, v[36:37]
	global_load_dwordx4 v[40:43], v[36:37], off offset:3072
	v_min_i32_e32 v36, 0x3f7, v122
	v_add_u32_e32 v36, 8, v36
	v_cmp_lt_i32_e32 vcc, -9, v122
	v_add_u32_e32 v8, v8, v97
	v_add_u32_e32 v12, v12, v97
	v_cndmask_b32_e32 v36, 0, v36, vcc
	v_add_u32_e32 v16, v16, v97
	v_add_u32_e32 v20, v20, v97
	v_add_u32_e32 v24, v24, v97
	v_add_u32_e32 v28, v28, v97
	v_add_u32_e32 v32, v32, v97
	v_add_u32_e32 v36, v36, v97
	v_ashrrev_i32_e32 v1, 31, v0
	v_ashrrev_i32_e32 v5, 31, v4
	v_ashrrev_i32_e32 v9, 31, v8
	v_ashrrev_i32_e32 v13, 31, v12
	v_ashrrev_i32_e32 v17, 31, v16
	v_ashrrev_i32_e32 v21, 31, v20
	v_ashrrev_i32_e32 v25, 31, v24
	v_ashrrev_i32_e32 v29, 31, v28
	v_ashrrev_i32_e32 v33, 31, v32
	v_ashrrev_i32_e32 v37, 31, v36
	v_lshlrev_b64 v[0:1], 13, v[0:1]
	v_lshlrev_b64 v[4:5], 13, v[4:5]
	v_lshlrev_b64 v[8:9], 13, v[8:9]
	v_lshlrev_b64 v[12:13], 13, v[12:13]
	v_lshlrev_b64 v[16:17], 13, v[16:17]
	v_lshlrev_b64 v[20:21], 13, v[20:21]
	v_lshlrev_b64 v[24:25], 13, v[24:25]
	v_lshlrev_b64 v[28:29], 13, v[28:29]
	v_lshlrev_b64 v[32:33], 13, v[32:33]
	v_lshlrev_b64 v[36:37], 13, v[36:37]
	v_lshl_add_u64 v[0:1], v[88:89], 0, v[0:1]
	v_lshl_add_u64 v[4:5], v[88:89], 0, v[4:5]
	v_lshl_add_u64 v[8:9], v[88:89], 0, v[8:9]
	v_lshl_add_u64 v[12:13], v[88:89], 0, v[12:13]
	v_lshl_add_u64 v[16:17], v[88:89], 0, v[16:17]
	v_lshl_add_u64 v[20:21], v[88:89], 0, v[20:21]
	v_lshl_add_u64 v[24:25], v[88:89], 0, v[24:25]
	v_lshl_add_u64 v[28:29], v[88:89], 0, v[28:29]
	v_lshl_add_u64 v[32:33], v[88:89], 0, v[32:33]
	v_lshl_add_u64 v[36:37], v[88:89], 0, v[36:37]
	global_load_dwordx4 v[0:3], v[0:1], off offset:3072
	s_nop 0
	global_load_dwordx4 v[4:7], v[4:5], off offset:3072
	s_nop 0
	global_load_dwordx4 v[8:11], v[8:9], off offset:3072
	s_nop 0
	global_load_dwordx4 v[12:15], v[12:13], off offset:3072
	s_nop 0
	global_load_dwordx4 v[16:19], v[16:17], off offset:3072
	s_nop 0
	global_load_dwordx4 v[20:23], v[20:21], off offset:3072
	s_nop 0
	global_load_dwordx4 v[24:27], v[24:25], off offset:3072
	s_nop 0
	global_load_dwordx4 v[28:31], v[28:29], off offset:3072
	s_nop 0
	global_load_dwordx4 v[32:35], v[32:33], off offset:3072
	s_nop 0
	global_load_dwordx4 v[36:39], v[36:37], off offset:3072
	s_waitcnt lgkmcnt(0)
	s_barrier
	s_branch .LBB0_541

.LBB0_541:
	v_xor_b32_e32 v44, s25, v75
	v_add_u32_e32 v52, v100, v106
	v_lshlrev_b32_e32 v125, 6, v44
	ds_read_b128 v[44:47], v52 offset:16384
	ds_read_b128 v[52:55], v52 offset:18432
	v_add_lshl_u32 v126, v125, v99, 7
	v_add_u32_e32 v56, 0, v126
	v_add_u32_e32 v48, v56, v106
	ds_read_b128 v[48:51], v48
	v_add_u32_e32 v57, v100, v107
	ds_read_b128 v[58:61], v57 offset:16384
	s_waitcnt lgkmcnt(1)
	v_mfma_f32_16x16x32_bf16 v[44:47], v[44:47], v[48:51], 0
	v_mfma_f32_16x16x32_bf16 v[48:51], v[52:55], v[48:51], 0
	v_add_u32_e32 v52, v56, v107
	ds_read_b128 v[62:65], v52
	ds_read_b128 v[90:93], v57 offset:18432
	s_waitcnt lgkmcnt(0)
	s_cmp_eq_u32 s25, 0
	s_cbranch_scc1 .Llru16_noba
	s_barrier
.Llru16_noba:
	ds_read_b128 v[54:57], v101
	v_mfma_f32_16x16x32_bf16 v[58:61], v[58:61], v[62:65], v[44:47]
	s_nop 2
	v_add_u32_e32 v45, v104, v126
	v_mfma_f32_16x16x32_bf16 v[46:49], v[90:93], v[62:65], v[48:51]
	s_waitcnt lgkmcnt(0)
	s_nop 1
	v_add_f32_e32 v44, v58, v54
	v_mul_f32_e32 v44, 0xbfb8aa3b, v44
	v_exp_f32_e32 v44, v44
	ds_read_b64 v[92:93], v45
	ds_read_b128 v[50:53], v102
	ds_read_b128 v[62:65], v103
	v_add_f32_e32 v57, v61, v57
	v_add_f32_e32 v44, 1.0, v44
	v_div_scale_f32 v45, s[0:1], v44, v44, 1.0
	v_rcp_f32_e32 v54, v45
	s_waitcnt lgkmcnt(1)
	v_add_f32_e32 v46, v46, v50
	v_mul_f32_e32 v46, 0xbfb8aa3b, v46
	v_add_f32_e32 v47, v47, v51
	v_fma_f32 v58, -v45, v54, 1.0
	v_fmac_f32_e32 v54, v58, v54
	v_div_scale_f32 v58, vcc, 1.0, v44, 1.0
	v_mul_f32_e32 v91, v58, v54
	v_fma_f32 v126, -v45, v91, v58
	v_fmac_f32_e32 v91, v126, v54
	v_fma_f32 v45, -v45, v91, v58
	v_div_fmas_f32 v45, v45, v54, v91
	v_div_fixup_f32 v44, v45, v44, 1.0
	v_mul_f32_e32 v44, 0xc1000000, v44
	s_waitcnt lgkmcnt(0)
	v_mul_f32_e32 v44, v62, v44
	v_mul_f32_e32 v44, 0x3fb8aa3b, v44
	v_exp_f32_e32 v44, v44
	v_mul_f32_e32 v47, 0xbfb8aa3b, v47
	v_mul_f32_e32 v57, 0xbfb8aa3b, v57
	v_exp_f32_e32 v57, v57
	v_fma_f32 v45, -v44, v44, 1.0
	v_max_f32_e32 v45, 0, v45
	v_cmp_gt_f32_e64 s[0:1], s10, v45
	v_mul_f32_e32 v54, 0x4f800000, v45
	v_add_f32_e32 v57, 1.0, v57
	v_cndmask_b32_e64 v58, v45, v54, s[0:1]
	v_sqrt_f32_e32 v45, v58
	v_exp_f32_e32 v54, v46
	v_add_f32_e32 v48, v48, v52
	v_add_f32_e32 v49, v49, v53
	v_add_u32_e32 v46, -1, v45
	v_fma_f32 v50, -v46, v45, v58
	v_cmp_ge_f32_e32 vcc, 0, v50
	v_add_f32_e32 v50, v59, v55
	v_mul_f32_e32 v50, 0xbfb8aa3b, v50
	v_exp_f32_e32 v50, v50
	v_add_u32_e32 v55, 1, v45
	v_cndmask_b32_e32 v46, v45, v46, vcc
	v_fma_f32 v45, -v55, v45, v58
	v_add_f32_e32 v50, 1.0, v50
	v_div_scale_f32 v59, s[26:27], v50, v50, 1.0
	v_rcp_f32_e32 v62, v59
	v_cmp_lt_f32_e32 vcc, 0, v45
	v_mul_f32_e32 v48, 0xbfb8aa3b, v48
	v_mul_f32_e32 v49, 0xbfb8aa3b, v49
	v_fma_f32 v45, -v59, v62, 1.0
	v_cndmask_b32_e32 v46, v46, v55, vcc
	v_fmac_f32_e32 v62, v45, v62
	v_div_scale_f32 v45, vcc, 1.0, v50, 1.0
	v_mul_f32_e32 v126, v45, v62
	v_fma_f32 v127, -v59, v126, v45
	v_fmac_f32_e32 v126, v127, v62
	v_fma_f32 v45, -v59, v126, v45
	v_div_fmas_f32 v45, v45, v62, v126
	v_div_fixup_f32 v45, v45, v50, 1.0
	v_mul_f32_e32 v45, 0xc1000000, v45
	v_mul_f32_e32 v45, v63, v45
	v_mul_f32_e32 v45, 0x3fb8aa3b, v45
	v_exp_f32_e32 v45, v45
	v_mul_f32_e32 v55, 0x37800000, v46
	v_cndmask_b32_e64 v46, v46, v55, s[0:1]
	v_cmp_class_f32_e32 vcc, v58, v169
	v_exp_f32_e32 v48, v48
	v_exp_f32_e32 v49, v49
	v_cndmask_b32_e32 v50, v46, v58, vcc
	v_fma_f32 v46, -v45, v45, 1.0
	v_max_f32_e32 v46, 0, v46
	v_cmp_gt_f32_e64 s[0:1], s10, v46
	v_mul_f32_e32 v55, 0x4f800000, v46
	v_pk_add_f32 v[48:49], v[48:49], 1.0 op_sel_hi:[1,0]
	v_cndmask_b32_e64 v58, v46, v55, s[0:1]
	v_sqrt_f32_e32 v46, v58
	v_exp_f32_e32 v55, v47
	v_lshlrev_b32_e32 v90, 16, v92
	v_and_b32_e32 v91, 0xffff0000, v92
	v_add_u32_e32 v47, -1, v46
	v_fma_f32 v51, -v47, v46, v58
	v_cmp_ge_f32_e32 vcc, 0, v51
	v_add_f32_e32 v51, v60, v56
	v_mul_f32_e32 v51, 0xbfb8aa3b, v51
	v_exp_f32_e32 v51, v51
	v_add_u32_e32 v56, 1, v46
	v_cndmask_b32_e32 v47, v46, v47, vcc
	v_fma_f32 v46, -v56, v46, v58
	v_add_f32_e32 v51, 1.0, v51
	v_div_scale_f32 v59, s[26:27], v51, v51, 1.0
	v_rcp_f32_e32 v60, v59
	v_cmp_lt_f32_e32 vcc, 0, v46
	v_pk_add_f32 v[54:55], v[54:55], 1.0 op_sel_hi:[1,0]
	v_lshlrev_b32_e32 v92, 16, v93
	v_fma_f32 v46, -v59, v60, 1.0
	v_cndmask_b32_e32 v47, v47, v56, vcc
	v_fmac_f32_e32 v60, v46, v60
	v_div_scale_f32 v46, vcc, 1.0, v51, 1.0
	v_mul_f32_e32 v62, v46, v60
	v_fma_f32 v63, -v59, v62, v46
	v_fmac_f32_e32 v62, v63, v60
	v_fma_f32 v46, -v59, v62, v46
	v_div_fmas_f32 v46, v46, v60, v62
	v_div_fixup_f32 v46, v46, v51, 1.0
	v_mul_f32_e32 v46, 0xc1000000, v46
	v_mul_f32_e32 v46, v64, v46
	v_mul_f32_e32 v46, 0x3fb8aa3b, v46
	v_exp_f32_e32 v46, v46
	v_mul_f32_e32 v56, 0x37800000, v47
	v_cndmask_b32_e64 v47, v47, v56, s[0:1]
	v_cmp_class_f32_e32 vcc, v58, v169
	v_div_scale_f32 v59, s[26:27], v57, v57, 1.0
	s_nop 0
	v_cndmask_b32_e32 v51, v47, v58, vcc
	v_fma_f32 v47, -v46, v46, 1.0
	v_max_f32_e32 v47, 0, v47
	v_cmp_gt_f32_e64 s[0:1], s10, v47
	v_mul_f32_e32 v56, 0x4f800000, v47
	v_rcp_f32_e32 v60, v59
	v_cndmask_b32_e64 v56, v47, v56, s[0:1]
	v_sqrt_f32_e32 v47, v56
	v_and_b32_e32 v93, 0xffff0000, v93
	v_add_u32_e32 v52, -1, v47
	v_fma_f32 v58, -v52, v47, v56
	v_cmp_ge_f32_e32 vcc, 0, v58
	v_add_u32_e32 v58, 1, v47
	s_nop 0
	v_cndmask_b32_e32 v52, v47, v52, vcc
	v_fma_f32 v47, -v58, v47, v56
	v_cmp_lt_f32_e32 vcc, 0, v47
	v_fma_f32 v47, -v59, v60, 1.0
	v_fmac_f32_e32 v60, v47, v60
	v_cndmask_b32_e32 v52, v52, v58, vcc
	v_div_scale_f32 v47, vcc, 1.0, v57, 1.0
	v_mul_f32_e32 v61, v47, v60
	v_fma_f32 v62, -v59, v61, v47
	v_fmac_f32_e32 v61, v62, v60
	v_fma_f32 v47, -v59, v61, v47
	v_div_fmas_f32 v47, v47, v60, v61
	v_div_fixup_f32 v47, v47, v57, 1.0
	v_mul_f32_e32 v47, 0xc1000000, v47
	v_mul_f32_e32 v47, v65, v47
	v_mul_f32_e32 v47, 0x3fb8aa3b, v47
	v_exp_f32_e32 v47, v47
	v_mul_f32_e32 v58, 0x37800000, v52
	v_cndmask_b32_e64 v52, v52, v58, s[0:1]
	v_cmp_class_f32_e32 vcc, v56, v169
	s_nop 1
	v_cndmask_b32_e32 v52, v52, v56, vcc
	v_fma_f32 v56, -v47, v47, 1.0
	v_max_f32_e32 v56, 0, v56
	v_cmp_gt_f32_e32 vcc, s10, v56
	v_mul_f32_e32 v57, 0x4f800000, v56
	s_nop 0
	v_cndmask_b32_e32 v56, v56, v57, vcc
	v_sqrt_f32_e32 v57, v56
	s_nop 0
	v_add_u32_e32 v53, -1, v57
	v_fma_f32 v58, -v53, v57, v56
	v_cmp_ge_f32_e64 s[0:1], 0, v58
	v_add_u32_e32 v58, 1, v57
	s_nop 0
	v_cndmask_b32_e64 v53, v57, v53, s[0:1]
	v_fma_f32 v57, -v58, v57, v56
	v_cmp_lt_f32_e64 s[0:1], 0, v57
	s_nop 1
	v_cndmask_b32_e64 v53, v53, v58, s[0:1]
	v_mul_f32_e32 v57, 0x37800000, v53
	v_cndmask_b32_e32 v53, v53, v57, vcc
	v_div_scale_f32 v57, s[0:1], v49, v49, 1.0
	v_rcp_f32_e32 v58, v57
	v_cmp_class_f32_e32 vcc, v56, v169
	s_nop 1
	v_cndmask_b32_e32 v53, v53, v56, vcc
	v_fma_f32 v56, -v57, v58, 1.0
	v_fmac_f32_e32 v58, v56, v58
	v_div_scale_f32 v56, vcc, 1.0, v49, 1.0
	v_mul_f32_e32 v59, v56, v58
	v_fma_f32 v60, -v57, v59, v56
	v_fmac_f32_e32 v59, v60, v58
	v_fma_f32 v56, -v57, v59, v56
	v_div_scale_f32 v57, s[0:1], v48, v48, 1.0
	v_rcp_f32_e32 v60, v57
	v_div_fmas_f32 v56, v56, v58, v59
	v_div_fixup_f32 v49, v56, v49, 1.0
	v_fma_f32 v56, -v57, v60, 1.0
	v_fmac_f32_e32 v60, v56, v60
	v_div_scale_f32 v56, vcc, 1.0, v48, 1.0
	v_mul_f32_e32 v58, v56, v60
	v_fma_f32 v59, -v57, v58, v56
	v_fmac_f32_e32 v58, v59, v60
	v_fma_f32 v56, -v57, v58, v56
	v_div_scale_f32 v57, s[0:1], v55, v55, 1.0
	v_rcp_f32_e32 v59, v57
	v_div_fmas_f32 v56, v56, v60, v58
	v_div_fixup_f32 v48, v56, v48, 1.0
	v_pk_mul_f32 v[48:49], v[48:49], v[52:53]
	v_fma_f32 v56, -v57, v59, 1.0
	v_fmac_f32_e32 v59, v56, v59
	v_div_scale_f32 v56, vcc, 1.0, v55, 1.0
	v_mul_f32_e32 v58, v56, v59
	v_fma_f32 v60, -v57, v58, v56
	v_fmac_f32_e32 v58, v60, v59
	v_fma_f32 v56, -v57, v58, v56
	v_div_scale_f32 v57, s[0:1], v54, v54, 1.0
	v_rcp_f32_e32 v60, v57
	v_div_fmas_f32 v56, v56, v59, v58
	v_div_fixup_f32 v55, v56, v55, 1.0
	v_fma_f32 v56, -v57, v60, 1.0
	v_fmac_f32_e32 v60, v56, v60
	v_div_scale_f32 v56, vcc, 1.0, v54, 1.0
	v_mul_f32_e32 v58, v56, v60
	v_fma_f32 v59, -v57, v58, v56
	v_fmac_f32_e32 v58, v59, v60
	v_fma_f32 v56, -v57, v58, v56
	v_div_fmas_f32 v56, v56, v60, v58
	v_div_fixup_f32 v54, v56, v54, 1.0
	v_pk_mul_f32 v[54:55], v[54:55], v[50:51]
	v_pk_mul_f32 v[50:51], v[48:49], v[92:93]
	v_pk_mul_f32 v[48:49], v[54:55], v[90:91]
	ds_write_b128 v105, v[44:47] offset:32768
	ds_write_b128 v105, v[48:51] offset:50176
	s_waitcnt lgkmcnt(0)
	s_barrier
	s_and_saveexec_b64 s[0:1], s[36:37]
	s_cbranch_execz .LBB0_540
	s_mov_b32 s26, 0
	s_and_b64 s[28:29], s[38:39], exec
	s_cbranch_scc0 .Lscan16_rinit
	v_mov_b32_e32 v44, v74
	ds_read_b32 v46, v44 offset:32768
	ds_read_b32 v47, v44 offset:50176
	ds_read_b32 v50, v44 offset:32848
	ds_read_b32 v51, v44 offset:50256
	ds_read_b32 v54, v44 offset:32928
	ds_read_b32 v55, v44 offset:50336
	ds_read_b32 v58, v44 offset:33008
	ds_read_b32 v59, v44 offset:50416
	ds_read_b32 v62, v44 offset:32768
	ds_read_b32 v63, v44 offset:32768
	ds_read_b32 v90, v44 offset:32768
	ds_read_b32 v91, v44 offset:32768
